# P3: upper-half blocks run the VALU-bound GLA chunk-summary items before the q/kv GEMM streams (co-resident blocks overlap MFMA-bound and VALU-bound work)
# baseline (speedup 1.0000x reference)
.LBB0_601:
	s_or_b64 exec, exec, s[0:1]
	s_mov_b32 s99, 0
.Lp3_gemm:
	v_readlane_b32 s0, v255, 40
	v_readlane_b32 s2, v253, 35
	v_readlane_b32 s1, v255, 41
	s_mul_i32 s0, s2, 0x60
	v_writelane_b32 v255, s0, 40
	v_mov_b32_e32 v2, v193
	s_waitcnt lgkmcnt(0)
	v_writelane_b32 v255, s1, 41
	v_readlane_b32 s0, v254, 37
	v_readlane_b32 s1, v254, 38
	s_and_b64 vcc, exec, s[0:1]
	s_barrier
	s_cmp_lg_u32 s99, 0
	s_cbranch_scc1 .Lp3_go
	s_cmpk_lg_i32 s50, 0x200
	s_cbranch_scc1 .Lp3_go
	v_readlane_b32 s98, v252, 0
	s_nop 0
	s_cmpk_lt_i32 s98, 0x100
	s_cbranch_scc1 .Lp3_go
	s_mov_b32 s99, 1
	s_branch .LBB0_669
.Lp3_go:
	v_readlane_b32 s3, v253, 36
	s_cbranch_vccz .LBB0_632
	v_readlane_b32 s0, v254, 44
	v_readlane_b32 s1, v254, 45
	v_ashrrev_i32_e32 v16, 3, v2
	s_movk_i32 s21, 0x840
	v_mov_b64_e32 v[4:5], s[0:1]
	v_mad_i64_i32 v[4:5], s[0:1], v16, s21, v[4:5]
	v_readlane_b32 s0, v254, 50
	v_readlane_b32 s1, v254, 51
	v_xor_b32_e32 v0, v16, v2
	s_movk_i32 s20, 0x600
	v_mov_b64_e32 v[6:7], s[0:1]
	v_lshlrev_b32_e32 v0, 4, v0
	v_mad_i64_i32 v[6:7], s[0:1], v16, s20, v[6:7]
	v_lshl_add_u32 v102, v2, 4, 0
	v_and_b32_e32 v0, 0x70, v0
	v_readfirstlane_b32 s0, v102
	v_lshl_add_u64 v[4:5], v[4:5], 0, v[0:1]
	s_mov_b32 m0, s0
	s_mov_b64 s[0:1], 0x10800
	v_add_u32_e32 v103, 0x1000, v102
	v_lshl_add_u64 v[8:9], v[4:5], 0, s[0:1]
	v_readfirstlane_b32 s0, v103
	s_barrier
	global_load_lds_dwordx4 v[4:5], off
	s_mov_b32 m0, s0
	s_mov_b64 s[0:1], 0x21000
	v_add_u32_e32 v104, 0x2000, v102
	global_load_lds_dwordx4 v[8:9], off
	v_lshl_add_u64 v[8:9], v[4:5], 0, s[0:1]
	v_readfirstlane_b32 s0, v104
	s_mov_b32 m0, s0
	s_mov_b64 s[0:1], 0x31800
	v_add_u32_e32 v105, 0x3000, v102
	v_lshl_add_u64 v[4:5], v[4:5], 0, s[0:1]
	v_readfirstlane_b32 s0, v105
	global_load_lds_dwordx4 v[8:9], off
	s_mov_b32 m0, s0
	v_add_u32_e32 v106, 0x4000, v102
	v_cmp_gt_i32_e32 vcc, 64, v16
	v_mov_b32_e32 v3, 0x6000
	global_load_lds_dwordx4 v[4:5], off
	v_lshl_add_u64 v[4:5], v[6:7], 0, v[0:1]
	v_readfirstlane_b32 s0, v106
	v_cndmask_b32_e32 v6, 0, v3, vcc
	v_add_u32_e32 v107, 0x5000, v102
	s_mov_b32 m0, s0
	v_lshlrev_b32_e32 v8, 1, v6
	v_mov_b32_e32 v9, v1
	v_readfirstlane_b32 s0, v107
	global_load_lds_dwordx4 v[4:5], off
	v_lshl_add_u64 v[10:11], v[4:5], 0, v[8:9]
	s_mov_b32 m0, s0
	v_cmp_gt_i32_e32 vcc, 32, v16
	v_mov_b32_e32 v3, 0xc000
	global_load_lds_dwordx4 v[10:11], off
	v_cndmask_b32_e32 v10, 0, v3, vcc
	v_add_u32_e32 v108, 0x6000, v102
	v_lshlrev_b32_e32 v12, 1, v10
	v_mov_b32_e32 v13, v1
	v_readfirstlane_b32 s0, v108
	v_lshl_add_u64 v[4:5], v[4:5], 0, v[12:13]
	s_mov_b32 m0, s0
	v_readlane_b32 s0, v255, 40
	global_load_lds_dwordx4 v[4:5], off
	v_readlane_b32 s1, v255, 41
	v_readlane_b32 s4, v252, 25
	v_ashrrev_i32_e32 v7, 7, v2
	s_lshl_b64 s[0:1], s[0:1], 2
	v_readlane_b32 s8, v252, 29
	v_readlane_b32 s12, v252, 33
	v_bfe_u32 v4, v2, 4, 2
	v_and_b32_e32 v5, 15, v2
	v_bfe_u32 v11, v2, 6, 1
	v_lshlrev_b32_e32 v19, 6, v7
	v_readlane_b32 s9, v252, 30
	v_readlane_b32 s13, v252, 34
	s_add_u32 s8, s12, s0
	v_lshlrev_b32_e32 v14, 2, v5
	v_readlane_b32 s0, v255, 36
	v_mul_u32_u24_e32 v18, 48, v11
	v_lshl_or_b32 v19, v4, 2, v19
	v_mul_u32_u24_e32 v20, 0xc0, v11
	v_or_b32_e32 v11, v11, v4
	s_movk_i32 s2, 0x190
	s_addc_u32 s9, s13, s1
	v_lshrrev_b32_e32 v3, 4, v2
	v_add_u32_e32 v17, s0, v14
	v_and_b32_e32 v15, 7, v2
	v_cmp_eq_u32_e64 s[0:1], 0, v11
	v_lshlrev_b32_e32 v11, 8, v7
	v_lshlrev_b32_e32 v110, 13, v7
	v_mul_lo_u32 v7, v19, s2
	v_readlane_b32 s2, v254, 46
	v_bitop3_b32 v3, v3, v15, 3 bitop3:0x6c
	v_readlane_b32 s3, v254, 47
	v_or_b32_e32 v18, v18, v5
	v_lshlrev_b32_e32 v109, 4, v3
	v_lshlrev_b32_e32 v111, 7, v5
	v_bitop3_b32 v3, v4, v15, 4 bitop3:0x36
	v_mov_b64_e32 v[4:5], s[2:3]
	v_mad_i64_i32 v[4:5], s[2:3], v16, s20, v[4:5]
	v_readlane_b32 s2, v254, 40
	v_readlane_b32 s3, v254, 41
	v_add3_u32 v20, 0, v14, v20
	v_lshl_add_u64 v[80:81], v[4:5], 0, v[0:1]
	v_mov_b64_e32 v[14:15], s[2:3]
	v_mad_i64_i32 v[14:15], s[2:3], v16, s21, v[14:15]
	v_lshl_add_u64 v[78:79], v[14:15], 0, v[0:1]
	v_bitop3_b32 v0, v16, 7, v2 bitop3:0x48
	v_lshlrev_b32_e32 v0, 4, v0
	v_lshlrev_b32_e32 v113, 4, v3
	v_mad_i64_i32 v[2:3], s[2:3], v16, s21, v[0:1]
	v_lshl_add_u64 v[82:83], s[48:49], 0, v[2:3]
	v_mad_i64_i32 v[2:3], s[2:3], v16, s20, 0
	v_readlane_b32 s2, v255, 17
	v_readlane_b32 s5, v252, 26
	v_readlane_b32 s6, v252, 27
	v_readlane_b32 s7, v252, 28
	v_or_b32_e32 v2, v2, v0
	v_readlane_b32 s3, v255, 18
	v_lshl_add_u64 v[4:5], v[2:3], 0, v[8:9]
	v_readlane_b32 s4, v254, 48
	v_lshl_add_u64 v[84:85], s[2:3], 0, v[2:3]
	v_lshl_add_u64 v[2:3], v[2:3], 0, v[12:13]
	v_readlane_b32 s6, v254, 42
	v_lshlrev_b32_e32 v112, 7, v18
	v_lshl_add_u64 v[86:87], s[2:3], 0, v[4:5]
	v_lshl_add_u64 v[88:89], s[2:3], 0, v[2:3]
	v_add_u32_e32 v114, v20, v7
	v_lshlrev_b32_e32 v90, 1, v6
	v_lshlrev_b32_e32 v92, 1, v10
	v_add_u32_e32 v115, v17, v11
	v_readlane_b32 s5, v254, 49
	v_readlane_b32 s7, v254, 43
	v_readlane_b32 s2, v254, 36
	v_readlane_b32 s10, v252, 31
	v_readlane_b32 s11, v252, 32
	v_readlane_b32 s14, v252, 35
	v_readlane_b32 s15, v252, 36
	v_readlane_b32 s16, v252, 37
	v_readlane_b32 s17, v252, 38
	v_readlane_b32 s18, v252, 39
	v_readlane_b32 s19, v252, 40
	s_branch .LBB0_604

.LBB0_669:
	v_readlane_b32 s1, v253, 32
	v_readlane_b32 s4, v252, 25
	s_lshl_b32 s0, s1, 14
	v_readlane_b32 s16, v252, 37
	v_readlane_b32 s17, v252, 38
	s_add_u32 s24, s16, s0
	v_readlane_b32 s2, v253, 35
	s_addc_u32 s25, s17, 0
	v_readlane_b32 s3, v253, 36
	s_or_b32 s0, s1, 1
	s_lshl_b32 s4, s2, 9
	s_lshl_b32 s1, s0, 14
	v_readlane_b32 s2, v255, 1
	s_add_u32 s26, s16, s1
	v_readlane_b32 s3, v255, 2
	s_addc_u32 s27, s17, 0
	s_andn2_b64 vcc, exec, s[2:3]
	s_lshl_b32 s28, s0, 8
	v_readlane_b32 s5, v252, 26
	v_readlane_b32 s6, v252, 27
	v_readlane_b32 s7, v252, 28
	v_readlane_b32 s8, v252, 29
	v_readlane_b32 s9, v252, 30
	v_readlane_b32 s10, v252, 31
	v_readlane_b32 s11, v252, 32
	v_readlane_b32 s12, v252, 33
	v_readlane_b32 s13, v252, 34
	v_readlane_b32 s14, v252, 35
	v_readlane_b32 s15, v252, 36
	v_readlane_b32 s18, v252, 39
	v_readlane_b32 s19, v252, 40
	s_cbranch_vccnz .LBB0_682
	s_cmp_eq_u32 s99, 2
	s_cbranch_scc1 .LBB0_682
	v_readlane_b32 s10, v255, 37
	s_lshl_b32 s5, s10, 6
	s_lshl_b32 s8, s50, 6
	v_readlane_b32 s9, v255, 38
	s_branch .LBB0_672

.LBB0_682:
	s_cmp_eq_u32 s99, 1
	s_cbranch_scc0 .Lp3_done
	s_mov_b32 s99, 2
	s_branch .Lp3_gemm
